# attention: LDS read hoist + unpacked pk f32 + canonicalizing v_max removed (85) with MFMA-result pads re-derived
# baseline (speedup 1.0000x reference)
.LBB0_1055:
	v_add3_u32 v83, s18, v186, v188
	ds_read_b128 v[212:215], v83 offset:128
	ds_read_b128 v[84:87], v83
	ds_read_b128 v[92:95], v83 offset:64
	s_waitcnt lgkmcnt(1)
	v_mfma_f32_16x16x32_bf16 v[88:91], v[84:87], v[0:3], 0
	ds_read_b128 v[98:101], v83 offset:3392
	ds_read_b128 v[102:105], v83 offset:6720
	ds_read_b128 v[156:159], v83 offset:10048
	v_mfma_f32_16x16x32_bf16 v[84:87], v[84:87], v[12:15], 0
	ds_read_b128 v[216:219], v83 offset:3328
	s_waitcnt lgkmcnt(3)
	v_mfma_f32_16x16x32_bf16 v[88:91], v[92:95], v[4:7], v[88:91]
	v_mfma_f32_16x16x32_bf16 v[84:87], v[92:95], v[16:19], v[84:87]
	s_waitcnt lgkmcnt(0)
	v_mfma_f32_16x16x32_bf16 v[160:163], v[212:215], v[8:11], v[88:91]
	v_mfma_f32_16x16x32_bf16 v[90:93], v[212:215], v[20:23], v[84:87]
	ds_read_b128 v[212:215], v83 offset:3456
	s_nop 3
	s_waitcnt lgkmcnt(0)
	v_mfma_f32_16x16x32_bf16 v[94:97], v[216:219], v[0:3], 0
	s_nop 0
	v_mfma_f32_16x16x32_bf16 v[84:87], v[216:219], v[12:15], 0
	ds_read_b128 v[216:219], v83 offset:6656
	v_mfma_f32_16x16x32_bf16 v[94:97], v[98:101], v[4:7], v[94:97]
	v_mfma_f32_16x16x32_bf16 v[84:87], v[98:101], v[16:19], v[84:87]
	s_waitcnt lgkmcnt(0)
	v_mfma_f32_16x16x32_bf16 v[166:169], v[212:215], v[8:11], v[94:97]
	v_mfma_f32_16x16x32_bf16 v[94:97], v[212:215], v[20:23], v[84:87]
	ds_read_b128 v[212:215], v83 offset:6784
	s_nop 3
	s_waitcnt lgkmcnt(0)
	v_mfma_f32_16x16x32_bf16 v[98:101], v[216:219], v[0:3], 0
	v_mfma_f32_16x16x32_bf16 v[84:87], v[216:219], v[12:15], 0
	ds_read_b128 v[216:219], v83 offset:9984
	v_mfma_f32_16x16x32_bf16 v[98:101], v[102:105], v[4:7], v[98:101]
	v_mfma_f32_16x16x32_bf16 v[84:87], v[102:105], v[16:19], v[84:87]
	s_waitcnt lgkmcnt(0)
	v_mfma_f32_16x16x32_bf16 v[174:177], v[212:215], v[8:11], v[98:101]
	v_mfma_f32_16x16x32_bf16 v[98:101], v[212:215], v[20:23], v[84:87]
	s_nop 3
	s_waitcnt lgkmcnt(0)
	v_mfma_f32_16x16x32_bf16 v[102:105], v[216:219], v[0:3], 0
	v_mfma_f32_16x16x32_bf16 v[84:87], v[216:219], v[12:15], 0
	v_mfma_f32_16x16x32_bf16 v[102:105], v[156:159], v[4:7], v[102:105]
	v_mfma_f32_16x16x32_bf16 v[84:87], v[156:159], v[16:19], v[84:87]
	ds_read_b128 v[156:159], v83 offset:10112
	s_waitcnt lgkmcnt(0)
	v_mfma_f32_16x16x32_bf16 v[192:195], v[156:159], v[8:11], v[102:105]
	v_mfma_f32_16x16x32_bf16 v[102:105], v[156:159], v[20:23], v[84:87]
	v_max_f32_e32 v153, v90, v91
	v_max_f32_e32 v83, v160, v161
	s_nop 1
	v_max_f32_e32 v84, v162, v163
	v_max_f32_e32 v85, v168, v169
	v_max3_f32 v85, v166, v167, v85
	v_max3_f32 v83, v83, v84, v85
	v_max_f32_e32 v84, v176, v177
	v_max_f32_e32 v86, v194, v194
	v_max_f32_e32 v85, v86, v195
	v_max3_f32 v84, v174, v175, v84
	v_max3_f32 v85, v192, v193, v85
	v_max3_f32 v83, v83, v84, v85
	s_waitcnt lgkmcnt(0)
	v_mov_b32_e32 v84, v83
	s_nop 1
	v_permlane16_swap_b32_e32 v83, v84
	v_max_f32_e32 v83, v83, v84
	v_mov_b32_e32 v84, v83
	s_nop 1
	v_permlane32_swap_b32_e32 v83, v84
	v_max3_f32 v143, v82, v83, v84
	v_sub_f32_e32 v82, v82, v143
	v_exp_f32_e32 v158, v82
	v_sub_f32_e32 v82, v160, v143
	v_exp_f32_e32 v152, v82
	v_sub_f32_e32 v82, v161, v143
	v_exp_f32_e32 v156, v82
	v_sub_f32_e32 v82, v162, v143
	v_exp_f32_e32 v160, v82
	v_sub_f32_e32 v82, v163, v143
	v_exp_f32_e32 v162, v82
	v_sub_f32_e32 v82, v166, v143
	v_exp_f32_e32 v164, v82
	v_sub_f32_e32 v82, v167, v143
	v_exp_f32_e32 v166, v82
	v_sub_f32_e32 v82, v168, v143
	v_exp_f32_e32 v168, v82
	v_sub_f32_e32 v82, v169, v143
	v_exp_f32_e32 v170, v82
	v_sub_f32_e32 v82, v174, v143
	v_exp_f32_e32 v172, v82
	v_sub_f32_e32 v82, v175, v143
	v_exp_f32_e32 v174, v82
	v_sub_f32_e32 v82, v176, v143
	v_exp_f32_e32 v176, v82
	v_sub_f32_e32 v82, v177, v143
	v_exp_f32_e32 v178, v82
	v_sub_f32_e32 v82, v192, v143
	v_exp_f32_e32 v180, v82
	v_sub_f32_e32 v82, v193, v143
	v_exp_f32_e32 v182, v82
	v_sub_f32_e32 v82, v194, v143
	v_exp_f32_e32 v192, v82
	v_sub_f32_e32 v82, v195, v143
	v_exp_f32_e32 v194, v82
	v_mul_f32_e32 v84, v68, v158
	v_mul_f32_e32 v85, v69, v158
	v_mul_f32_e32 v82, v66, v158
	v_mul_f32_e32 v83, v67, v158
	v_mul_f32_e32 v88, v72, v158
	v_mul_f32_e32 v89, v73, v158
	v_mul_f32_e32 v86, v70, v158
	v_mul_f32_e32 v87, v71, v158
	v_mul_f32_e32 v76, v76, v158
	v_mul_f32_e32 v77, v77, v158
	v_mul_f32_e32 v74, v74, v158
	v_mul_f32_e32 v75, v75, v158
	v_mul_f32_e32 v68, v80, v158
	v_mul_f32_e32 v69, v81, v158
	v_mul_f32_e32 v66, v78, v158
	v_mul_f32_e32 v67, v79, v158
	v_max_f32_e32 v157, v92, v93
	v_max_f32_e32 v159, v96, v97
	v_max3_f32 v159, v94, v95, v159
	v_max3_f32 v153, v153, v157, v159
	v_max_f32_e32 v157, v100, v101
	v_max_f32_e32 v159, v104, v105
	v_max3_f32 v157, v98, v99, v157
	v_max3_f32 v159, v102, v103, v159
	v_max3_f32 v153, v153, v157, v159
	v_cvt_pk_bf16_f32 v70, v152, v156
	v_cvt_pk_bf16_f32 v71, v160, v162
	v_cvt_pk_bf16_f32 v72, v164, v166
	v_cvt_pk_bf16_f32 v73, v168, v170
	s_waitcnt lgkmcnt(0)
	v_mov_b32_e32 v157, v153
	s_nop 1
	v_permlane16_swap_b32_e32 v153, v157
	v_max_f32_e32 v153, v153, v157
	v_mov_b32_e32 v157, v153
	s_nop 1
	v_permlane32_swap_b32_e32 v153, v157
	v_max3_f32 v191, v127, v153, v157
	v_sub_f32_e32 v90, v90, v191
	v_exp_f32_e32 v153, v90
	v_sub_f32_e32 v90, v91, v191
	v_exp_f32_e32 v157, v90
	v_sub_f32_e32 v90, v92, v191
	v_exp_f32_e32 v161, v90
	v_sub_f32_e32 v90, v93, v191
	v_exp_f32_e32 v163, v90
	v_sub_f32_e32 v90, v94, v191
	v_exp_f32_e32 v165, v90
	v_sub_f32_e32 v90, v95, v191
	v_exp_f32_e32 v167, v90
	v_add_f32_e32 v90, 0, v152
	v_add_f32_e32 v91, 0, v153
	v_sub_f32_e32 v92, v96, v191
	v_add_f32_e32 v90, v156, v90
	v_add_f32_e32 v91, v157, v91
	v_exp_f32_e32 v169, v92
	v_add_f32_e32 v90, v160, v90
	v_add_f32_e32 v91, v161, v91
	v_sub_f32_e32 v92, v97, v191
	v_add_f32_e32 v90, v162, v90
	v_add_f32_e32 v91, v163, v91
	v_exp_f32_e32 v171, v92
	v_sub_f32_e32 v92, v98, v191
	v_add_f32_e32 v90, v164, v90
	v_add_f32_e32 v91, v165, v91
	v_exp_f32_e32 v173, v92
	v_sub_f32_e32 v92, v99, v191
	v_add_f32_e32 v90, v166, v90
	v_add_f32_e32 v91, v167, v91
	v_exp_f32_e32 v175, v92
	v_sub_f32_e32 v92, v100, v191
	v_exp_f32_e32 v177, v92
	v_sub_f32_e32 v92, v101, v191
	v_add_f32_e32 v90, v168, v90
	v_add_f32_e32 v91, v169, v91
	v_exp_f32_e32 v179, v92
	v_sub_f32_e32 v92, v102, v191
	v_add_f32_e32 v90, v170, v90
	v_add_f32_e32 v91, v171, v91
	v_exp_f32_e32 v181, v92
	v_sub_f32_e32 v92, v103, v191
	v_add_f32_e32 v90, v172, v90
	v_add_f32_e32 v91, v173, v91
	v_exp_f32_e32 v183, v92
	v_sub_f32_e32 v92, v104, v191
	v_add_f32_e32 v90, v174, v90
	v_add_f32_e32 v91, v175, v91
	v_sub_f32_e32 v127, v127, v191
	v_exp_f32_e32 v193, v92
	v_sub_f32_e32 v92, v105, v191
	v_add_f32_e32 v90, v176, v90
	v_add_f32_e32 v91, v177, v91
	v_exp_f32_e32 v159, v127
	v_exp_f32_e32 v195, v92
	v_add_f32_e32 v90, v178, v90
	v_add_f32_e32 v91, v179, v91
	v_cvt_pk_bf16_f32 v78, v172, v174
	v_add_f32_e32 v90, v180, v90
	v_add_f32_e32 v91, v181, v91
	v_mov_b32_e32 v98, v159
	v_add_f32_e32 v90, v182, v90
	v_add_f32_e32 v91, v183, v91
	v_mul_f32_e32 v92, v52, v98
	v_mul_f32_e32 v93, v53, v98
	v_add_f32_e32 v90, v192, v90
	v_add_f32_e32 v91, v193, v91
	v_mul_f32_e32 v96, v56, v98
	v_mul_f32_e32 v97, v57, v98
	v_add_f32_e32 v90, v194, v90
	v_add_f32_e32 v91, v195, v91
	v_mul_f32_e32 v94, v54, v98
	v_mul_f32_e32 v95, v55, v98
	v_pk_fma_f32 v[150:151], v[150:151], v[158:159], v[90:91]
	v_mul_f32_e32 v90, v50, v98
	v_mul_f32_e32 v91, v51, v98
	v_mul_f32_e32 v60, v60, v98
	v_mul_f32_e32 v61, v61, v98
	v_mul_f32_e32 v58, v58, v98
	v_mul_f32_e32 v59, v59, v98
	v_mul_f32_e32 v52, v64, v98
	v_mul_f32_e32 v53, v65, v98
	v_mul_f32_e32 v50, v62, v98
	v_mul_f32_e32 v51, v63, v98
	v_lshlrev_b32_e32 v98, 1, v187
	v_add3_u32 v127, s18, v98, v189
	ds_read_b64_tr_b16 v[216:217], v127 offset:13384
	ds_read_b64_tr_b16 v[218:219], v127 offset:15944
	ds_read_b64_tr_b16 v[212:213], v127 offset:13376
	ds_read_b64_tr_b16 v[214:215], v127 offset:15936
	ds_read_b64_tr_b16 v[100:101], v127 offset:15872
	ds_read_b64_tr_b16 v[98:99], v127 offset:13312
	ds_read_b64_tr_b16 v[102:103], v127 offset:13320
	v_cvt_pk_bf16_f32 v54, v153, v157
	v_cvt_pk_bf16_f32 v55, v161, v163
	v_cvt_pk_bf16_f32 v56, v165, v167
	v_cvt_pk_bf16_f32 v57, v169, v171
	s_waitcnt lgkmcnt(1)
	v_mfma_f32_16x16x32_bf16 v[82:85], v[98:101], v[70:73], v[82:85]
	ds_read_b64_tr_b16 v[104:105], v127 offset:15880
	v_cvt_pk_bf16_f32 v79, v176, v178
	v_cvt_pk_bf16_f32 v80, v180, v182
	v_mfma_f32_16x16x32_bf16 v[90:93], v[98:101], v[54:57], v[90:93]
	v_cvt_pk_bf16_f32 v81, v192, v194
	v_cvt_pk_bf16_f32 v62, v173, v175
	s_waitcnt lgkmcnt(0)
	v_mfma_f32_16x16x32_bf16 v[74:77], v[212:215], v[70:73], v[74:77]
	v_cvt_pk_bf16_f32 v63, v177, v179
	v_cvt_pk_bf16_f32 v64, v181, v183
	v_cvt_pk_bf16_f32 v65, v193, v195
	v_mfma_f32_16x16x32_bf16 v[58:61], v[212:215], v[54:57], v[58:61]
	ds_read_b64_tr_b16 v[212:213], v127 offset:18432
	ds_read_b64_tr_b16 v[214:215], v127 offset:20992
	v_mfma_f32_16x16x32_bf16 v[86:89], v[102:105], v[70:73], v[86:89]
	ds_read_b64_tr_b16 v[220:221], v127 offset:18496
	ds_read_b64_tr_b16 v[222:223], v127 offset:21056
	v_mfma_f32_16x16x32_bf16 v[94:97], v[102:105], v[54:57], v[94:97]
	s_waitcnt lgkmcnt(0)
	v_mfma_f32_16x16x32_bf16 v[102:105], v[216:219], v[70:73], v[66:69]
	v_mfma_f32_16x16x32_bf16 v[98:101], v[216:219], v[54:57], v[50:53]
	s_nop 2
	ds_read_b64_tr_b16 v[54:55], v127 offset:18440
	ds_read_b64_tr_b16 v[56:57], v127 offset:21000
	s_waitcnt lgkmcnt(2)
	v_mfma_f32_16x16x32_bf16 v[66:69], v[212:215], v[78:81], v[82:85]
	s_nop 2
	s_waitcnt lgkmcnt(0)
	v_mfma_f32_16x16x32_bf16 v[74:77], v[220:223], v[78:81], v[74:77]
	v_mfma_f32_16x16x32_bf16 v[58:61], v[220:223], v[62:65], v[58:61]
	ds_read_b64_tr_b16 v[82:83], v127 offset:18504
	ds_read_b64_tr_b16 v[84:85], v127 offset:21064
	v_mov_b32_e32 v127, v191
	v_mfma_f32_16x16x32_bf16 v[50:53], v[212:215], v[62:65], v[90:93]
	v_mfma_f32_16x16x32_bf16 v[70:73], v[54:57], v[78:81], v[86:89]
	v_mfma_f32_16x16x32_bf16 v[54:57], v[54:57], v[62:65], v[94:97]
	s_waitcnt lgkmcnt(0)
	v_mfma_f32_16x16x32_bf16 v[78:81], v[82:85], v[78:81], v[102:105]
	v_mfma_f32_16x16x32_bf16 v[62:65], v[82:85], v[62:65], v[98:101]
	v_mov_b32_e32 v82, v143
	s_add_i32 s6, s48, -2
	s_cmp_ge_i32 s6, s47
	s_cbranch_scc1 .LBB0_1042
.LBB0_1056:
	s_and_b32 s6, s6, 3
	s_mulk_i32 s6, 0x5c00
	s_add_i32 s18, s6, 0
	v_add3_u32 v83, s18, v186, v188
	ds_read_b128 v[212:215], v83 offset:128
	ds_read_b128 v[84:87], v83
	ds_read_b128 v[92:95], v83 offset:64
	s_waitcnt lgkmcnt(1)
	v_mfma_f32_16x16x32_bf16 v[88:91], v[84:87], v[0:3], 0
	ds_read_b128 v[98:101], v83 offset:3392
	ds_read_b128 v[102:105], v83 offset:6720
	ds_read_b128 v[156:159], v83 offset:10048
	v_mfma_f32_16x16x32_bf16 v[84:87], v[84:87], v[12:15], 0
	ds_read_b128 v[216:219], v83 offset:3328
	s_waitcnt lgkmcnt(3)
	v_mfma_f32_16x16x32_bf16 v[88:91], v[92:95], v[4:7], v[88:91]
	v_mfma_f32_16x16x32_bf16 v[84:87], v[92:95], v[16:19], v[84:87]
	s_waitcnt lgkmcnt(0)
	v_mfma_f32_16x16x32_bf16 v[160:163], v[212:215], v[8:11], v[88:91]
	v_mfma_f32_16x16x32_bf16 v[90:93], v[212:215], v[20:23], v[84:87]
	ds_read_b128 v[212:215], v83 offset:3456
	s_nop 3
	s_waitcnt lgkmcnt(0)
	v_mfma_f32_16x16x32_bf16 v[94:97], v[216:219], v[0:3], 0
	s_nop 0
	v_mfma_f32_16x16x32_bf16 v[84:87], v[216:219], v[12:15], 0
	ds_read_b128 v[216:219], v83 offset:6656
	v_mfma_f32_16x16x32_bf16 v[94:97], v[98:101], v[4:7], v[94:97]
	v_mfma_f32_16x16x32_bf16 v[84:87], v[98:101], v[16:19], v[84:87]
	s_waitcnt lgkmcnt(0)
	v_mfma_f32_16x16x32_bf16 v[166:169], v[212:215], v[8:11], v[94:97]
	v_mfma_f32_16x16x32_bf16 v[94:97], v[212:215], v[20:23], v[84:87]
	ds_read_b128 v[212:215], v83 offset:6784
	s_nop 3
	s_waitcnt lgkmcnt(0)
	v_mfma_f32_16x16x32_bf16 v[98:101], v[216:219], v[0:3], 0
	v_mfma_f32_16x16x32_bf16 v[84:87], v[216:219], v[12:15], 0
	ds_read_b128 v[216:219], v83 offset:9984
	v_mfma_f32_16x16x32_bf16 v[98:101], v[102:105], v[4:7], v[98:101]
	v_mfma_f32_16x16x32_bf16 v[84:87], v[102:105], v[16:19], v[84:87]
	s_waitcnt lgkmcnt(0)
	v_mfma_f32_16x16x32_bf16 v[174:177], v[212:215], v[8:11], v[98:101]
	v_mfma_f32_16x16x32_bf16 v[98:101], v[212:215], v[20:23], v[84:87]
	s_nop 3
	s_waitcnt lgkmcnt(0)
	v_mfma_f32_16x16x32_bf16 v[102:105], v[216:219], v[0:3], 0
	v_mfma_f32_16x16x32_bf16 v[84:87], v[216:219], v[12:15], 0
	v_mfma_f32_16x16x32_bf16 v[102:105], v[156:159], v[4:7], v[102:105]
	v_mfma_f32_16x16x32_bf16 v[84:87], v[156:159], v[16:19], v[84:87]
	ds_read_b128 v[156:159], v83 offset:10112
	s_waitcnt lgkmcnt(0)
	v_mfma_f32_16x16x32_bf16 v[180:183], v[156:159], v[8:11], v[102:105]
	v_mfma_f32_16x16x32_bf16 v[102:105], v[156:159], v[20:23], v[84:87]
	v_max_f32_e32 v153, v90, v91
	v_max_f32_e32 v83, v160, v161
	s_nop 1
	v_max_f32_e32 v84, v162, v163
	v_max_f32_e32 v85, v168, v169
	v_max3_f32 v85, v166, v167, v85
	v_max3_f32 v83, v83, v84, v85
	v_max_f32_e32 v84, v176, v177
	v_max_f32_e32 v85, v182, v183
	v_max3_f32 v84, v174, v175, v84
	v_max3_f32 v85, v180, v181, v85
	v_max3_f32 v83, v83, v84, v85
	s_waitcnt lgkmcnt(0)
	v_mov_b32_e32 v84, v83
	s_nop 1
	v_permlane16_swap_b32_e32 v83, v84
	v_max_f32_e32 v83, v83, v84
	v_mov_b32_e32 v84, v83
	s_nop 1
	v_permlane32_swap_b32_e32 v83, v84
	v_max3_f32 v143, v82, v83, v84
	v_sub_f32_e32 v82, v82, v143
	v_exp_f32_e32 v158, v82
	v_sub_f32_e32 v82, v160, v143
	v_exp_f32_e32 v152, v82
	v_sub_f32_e32 v82, v161, v143
	v_exp_f32_e32 v156, v82
	v_sub_f32_e32 v82, v162, v143
	v_exp_f32_e32 v160, v82
	v_sub_f32_e32 v82, v163, v143
	v_exp_f32_e32 v162, v82
	v_sub_f32_e32 v82, v166, v143
	v_exp_f32_e32 v164, v82
	v_sub_f32_e32 v82, v167, v143
	v_exp_f32_e32 v166, v82
	v_sub_f32_e32 v82, v168, v143
	v_exp_f32_e32 v168, v82
	v_sub_f32_e32 v82, v169, v143
	v_exp_f32_e32 v170, v82
	v_sub_f32_e32 v82, v174, v143
	v_exp_f32_e32 v172, v82
	v_sub_f32_e32 v82, v175, v143
	v_exp_f32_e32 v174, v82
	v_sub_f32_e32 v82, v176, v143
	v_exp_f32_e32 v176, v82
	v_sub_f32_e32 v82, v177, v143
	v_exp_f32_e32 v178, v82
	v_sub_f32_e32 v82, v180, v143
	v_exp_f32_e32 v180, v82
	v_sub_f32_e32 v82, v181, v143
	v_exp_f32_e32 v192, v82
	v_sub_f32_e32 v82, v182, v143
	v_exp_f32_e32 v194, v82
	v_sub_f32_e32 v82, v183, v143
	v_exp_f32_e32 v196, v82
	v_mul_f32_e32 v84, v68, v158
	v_mul_f32_e32 v85, v69, v158
	v_mul_f32_e32 v82, v66, v158
	v_mul_f32_e32 v83, v67, v158
	v_mul_f32_e32 v88, v72, v158
	v_mul_f32_e32 v89, v73, v158
	v_mul_f32_e32 v86, v70, v158
	v_mul_f32_e32 v87, v71, v158
	v_mul_f32_e32 v76, v76, v158
	v_mul_f32_e32 v77, v77, v158
	v_mul_f32_e32 v74, v74, v158
	v_mul_f32_e32 v75, v75, v158
	v_mul_f32_e32 v68, v80, v158
	v_mul_f32_e32 v69, v81, v158
	v_mul_f32_e32 v66, v78, v158
	v_mul_f32_e32 v67, v79, v158
	v_max_f32_e32 v157, v92, v93
	v_max_f32_e32 v159, v96, v97
	v_max3_f32 v159, v94, v95, v159
	v_max3_f32 v153, v153, v157, v159
	v_max_f32_e32 v157, v100, v101
	v_max_f32_e32 v159, v104, v105
	v_max3_f32 v157, v98, v99, v157
	v_max3_f32 v159, v102, v103, v159
	v_max3_f32 v153, v153, v157, v159
	v_cvt_pk_bf16_f32 v70, v152, v156
	v_cvt_pk_bf16_f32 v71, v160, v162
	v_cvt_pk_bf16_f32 v72, v164, v166
	v_cvt_pk_bf16_f32 v73, v168, v170
	s_waitcnt lgkmcnt(0)
	v_mov_b32_e32 v157, v153
	s_nop 1
	v_permlane16_swap_b32_e32 v153, v157
	v_max_f32_e32 v153, v153, v157
	v_mov_b32_e32 v157, v153
	s_nop 1
	v_permlane32_swap_b32_e32 v153, v157
	v_max3_f32 v182, v127, v153, v157
	v_sub_f32_e32 v90, v90, v182
	v_exp_f32_e32 v153, v90
	v_sub_f32_e32 v90, v91, v182
	v_exp_f32_e32 v157, v90
	v_sub_f32_e32 v90, v92, v182
	v_exp_f32_e32 v161, v90
	v_sub_f32_e32 v90, v93, v182
	v_exp_f32_e32 v163, v90
	v_sub_f32_e32 v90, v94, v182
	v_exp_f32_e32 v165, v90
	v_sub_f32_e32 v90, v95, v182
	v_exp_f32_e32 v167, v90
	v_add_f32_e32 v90, 0, v152
	v_add_f32_e32 v91, 0, v153
	v_sub_f32_e32 v92, v96, v182
	v_add_f32_e32 v90, v156, v90
	v_add_f32_e32 v91, v157, v91
	v_exp_f32_e32 v169, v92
	v_add_f32_e32 v90, v160, v90
	v_add_f32_e32 v91, v161, v91
	v_sub_f32_e32 v92, v97, v182
	v_add_f32_e32 v90, v162, v90
	v_add_f32_e32 v91, v163, v91
	v_exp_f32_e32 v171, v92
	v_sub_f32_e32 v92, v98, v182
	v_add_f32_e32 v90, v164, v90
	v_add_f32_e32 v91, v165, v91
	v_exp_f32_e32 v173, v92
	v_sub_f32_e32 v92, v99, v182
	v_add_f32_e32 v90, v166, v90
	v_add_f32_e32 v91, v167, v91
	v_exp_f32_e32 v175, v92
	v_sub_f32_e32 v92, v100, v182
	v_exp_f32_e32 v177, v92
	v_sub_f32_e32 v92, v101, v182
	v_add_f32_e32 v90, v168, v90
	v_add_f32_e32 v91, v169, v91
	v_exp_f32_e32 v179, v92
	v_sub_f32_e32 v92, v102, v182
	v_add_f32_e32 v90, v170, v90
	v_add_f32_e32 v91, v171, v91
	v_exp_f32_e32 v181, v92
	v_sub_f32_e32 v92, v103, v182
	v_add_f32_e32 v90, v172, v90
	v_add_f32_e32 v91, v173, v91
	v_exp_f32_e32 v193, v92
	v_sub_f32_e32 v92, v104, v182
	v_add_f32_e32 v90, v174, v90
	v_add_f32_e32 v91, v175, v91
	v_sub_f32_e32 v127, v127, v182
	v_exp_f32_e32 v195, v92
	v_sub_f32_e32 v92, v105, v182
	v_add_f32_e32 v90, v176, v90
	v_add_f32_e32 v91, v177, v91
	v_exp_f32_e32 v159, v127
	v_exp_f32_e32 v197, v92
	v_add_f32_e32 v90, v178, v90
	v_add_f32_e32 v91, v179, v91
	v_cvt_pk_bf16_f32 v78, v172, v174
	v_add_f32_e32 v90, v180, v90
	v_add_f32_e32 v91, v181, v91
	v_mov_b32_e32 v98, v159
	v_add_f32_e32 v90, v192, v90
	v_add_f32_e32 v91, v193, v91
	v_mul_f32_e32 v92, v52, v98
	v_mul_f32_e32 v93, v53, v98
	v_add_f32_e32 v90, v194, v90
	v_add_f32_e32 v91, v195, v91
	v_mul_f32_e32 v96, v56, v98
	v_mul_f32_e32 v97, v57, v98
	v_add_f32_e32 v90, v196, v90
	v_add_f32_e32 v91, v197, v91
	v_mul_f32_e32 v94, v54, v98
	v_mul_f32_e32 v95, v55, v98
	v_pk_fma_f32 v[150:151], v[150:151], v[158:159], v[90:91]
	v_mul_f32_e32 v90, v50, v98
	v_mul_f32_e32 v91, v51, v98
	v_mul_f32_e32 v60, v60, v98
	v_mul_f32_e32 v61, v61, v98
	v_mul_f32_e32 v58, v58, v98
	v_mul_f32_e32 v59, v59, v98
	v_mul_f32_e32 v52, v64, v98
	v_mul_f32_e32 v53, v65, v98
	v_mul_f32_e32 v50, v62, v98
	v_mul_f32_e32 v51, v63, v98
	v_lshlrev_b32_e32 v98, 1, v187
	v_add3_u32 v127, s18, v98, v189
	ds_read_b64_tr_b16 v[216:217], v127 offset:13384
	ds_read_b64_tr_b16 v[218:219], v127 offset:15944
	ds_read_b64_tr_b16 v[212:213], v127 offset:13376
	ds_read_b64_tr_b16 v[214:215], v127 offset:15936
	ds_read_b64_tr_b16 v[100:101], v127 offset:15872
	ds_read_b64_tr_b16 v[98:99], v127 offset:13312
	ds_read_b64_tr_b16 v[102:103], v127 offset:13320
	v_cvt_pk_bf16_f32 v54, v153, v157
	v_cvt_pk_bf16_f32 v55, v161, v163
	v_cvt_pk_bf16_f32 v56, v165, v167
	v_cvt_pk_bf16_f32 v57, v169, v171
	s_waitcnt lgkmcnt(1)
	v_mfma_f32_16x16x32_bf16 v[82:85], v[98:101], v[70:73], v[82:85]
	ds_read_b64_tr_b16 v[104:105], v127 offset:15880
	v_cvt_pk_bf16_f32 v79, v176, v178
	v_cvt_pk_bf16_f32 v80, v180, v192
	v_mfma_f32_16x16x32_bf16 v[90:93], v[98:101], v[54:57], v[90:93]
	v_cvt_pk_bf16_f32 v81, v194, v196
	v_cvt_pk_bf16_f32 v62, v173, v175
	s_waitcnt lgkmcnt(0)
	v_mfma_f32_16x16x32_bf16 v[74:77], v[212:215], v[70:73], v[74:77]
	v_cvt_pk_bf16_f32 v63, v177, v179
	v_cvt_pk_bf16_f32 v64, v181, v193
	v_cvt_pk_bf16_f32 v65, v195, v197
	v_mfma_f32_16x16x32_bf16 v[58:61], v[212:215], v[54:57], v[58:61]
	ds_read_b64_tr_b16 v[212:213], v127 offset:18432
	ds_read_b64_tr_b16 v[214:215], v127 offset:20992
	v_mfma_f32_16x16x32_bf16 v[86:89], v[102:105], v[70:73], v[86:89]
	ds_read_b64_tr_b16 v[220:221], v127 offset:18496
	ds_read_b64_tr_b16 v[222:223], v127 offset:21056
	v_mfma_f32_16x16x32_bf16 v[94:97], v[102:105], v[54:57], v[94:97]
	s_waitcnt lgkmcnt(0)
	v_mfma_f32_16x16x32_bf16 v[102:105], v[216:219], v[70:73], v[66:69]
	v_mfma_f32_16x16x32_bf16 v[98:101], v[216:219], v[54:57], v[50:53]
	s_nop 2
	ds_read_b64_tr_b16 v[54:55], v127 offset:18440
	ds_read_b64_tr_b16 v[56:57], v127 offset:21000
	s_waitcnt lgkmcnt(2)
	v_mfma_f32_16x16x32_bf16 v[66:69], v[212:215], v[78:81], v[82:85]
	s_nop 2
	s_waitcnt lgkmcnt(0)
	v_mfma_f32_16x16x32_bf16 v[74:77], v[220:223], v[78:81], v[74:77]
	v_mfma_f32_16x16x32_bf16 v[58:61], v[220:223], v[62:65], v[58:61]
	ds_read_b64_tr_b16 v[82:83], v127 offset:18504
	ds_read_b64_tr_b16 v[84:85], v127 offset:21064
	v_mov_b32_e32 v127, v182
	v_mfma_f32_16x16x32_bf16 v[50:53], v[212:215], v[62:65], v[90:93]
	v_mfma_f32_16x16x32_bf16 v[70:73], v[54:57], v[78:81], v[86:89]
	v_mfma_f32_16x16x32_bf16 v[54:57], v[54:57], v[62:65], v[94:97]
	s_waitcnt lgkmcnt(0)
	v_mfma_f32_16x16x32_bf16 v[78:81], v[82:85], v[78:81], v[102:105]
	v_mfma_f32_16x16x32_bf16 v[62:65], v[82:85], v[62:65], v[98:101]
	v_mov_b32_e32 v82, v143
	s_branch .LBB0_1042

.LBB0_1077:
	v_add3_u32 v83, s18, v186, v188
	ds_read_b128 v[212:215], v83 offset:128
	ds_read_b128 v[84:87], v83
	ds_read_b128 v[92:95], v83 offset:64
	s_waitcnt lgkmcnt(1)
	v_mfma_f32_16x16x32_bf16 v[88:91], v[84:87], v[8:11], 0
	ds_read_b128 v[98:101], v83 offset:3392
	ds_read_b128 v[102:105], v83 offset:6720
	ds_read_b128 v[144:147], v83 offset:10048
	v_mfma_f32_16x16x32_bf16 v[84:87], v[84:87], v[12:15], 0
	ds_read_b128 v[216:219], v83 offset:3328
	s_waitcnt lgkmcnt(3)
	v_mfma_f32_16x16x32_bf16 v[88:91], v[92:95], v[0:3], v[88:91]
	v_mfma_f32_16x16x32_bf16 v[84:87], v[92:95], v[16:19], v[84:87]
	s_waitcnt lgkmcnt(0)
	v_mfma_f32_16x16x32_bf16 v[150:153], v[212:215], v[4:7], v[88:91]
	v_mfma_f32_16x16x32_bf16 v[90:93], v[212:215], v[20:23], v[84:87]
	ds_read_b128 v[212:215], v83 offset:3456
	s_nop 3
	s_waitcnt lgkmcnt(0)
	v_mfma_f32_16x16x32_bf16 v[94:97], v[216:219], v[8:11], 0
	v_mfma_f32_16x16x32_bf16 v[84:87], v[216:219], v[12:15], 0
	ds_read_b128 v[216:219], v83 offset:6656
	v_mfma_f32_16x16x32_bf16 v[94:97], v[98:101], v[0:3], v[94:97]
	v_mfma_f32_16x16x32_bf16 v[84:87], v[98:101], v[16:19], v[84:87]
	s_waitcnt lgkmcnt(0)
	v_mfma_f32_16x16x32_bf16 v[158:161], v[212:215], v[4:7], v[94:97]
	v_mfma_f32_16x16x32_bf16 v[94:97], v[212:215], v[20:23], v[84:87]
	ds_read_b128 v[212:215], v83 offset:6784
	s_nop 3
	s_waitcnt lgkmcnt(0)
	v_mfma_f32_16x16x32_bf16 v[98:101], v[216:219], v[8:11], 0
	v_mfma_f32_16x16x32_bf16 v[84:87], v[216:219], v[12:15], 0
	ds_read_b128 v[216:219], v83 offset:9984
	v_mfma_f32_16x16x32_bf16 v[98:101], v[102:105], v[0:3], v[98:101]
	v_mfma_f32_16x16x32_bf16 v[84:87], v[102:105], v[16:19], v[84:87]
	s_waitcnt lgkmcnt(0)
	v_mfma_f32_16x16x32_bf16 v[166:169], v[212:215], v[4:7], v[98:101]
	v_mfma_f32_16x16x32_bf16 v[98:101], v[212:215], v[20:23], v[84:87]
	s_nop 3
	s_waitcnt lgkmcnt(0)
	v_mfma_f32_16x16x32_bf16 v[102:105], v[216:219], v[8:11], 0
	v_mfma_f32_16x16x32_bf16 v[84:87], v[216:219], v[12:15], 0
	v_mfma_f32_16x16x32_bf16 v[102:105], v[144:147], v[0:3], v[102:105]
	v_mfma_f32_16x16x32_bf16 v[84:87], v[144:147], v[16:19], v[84:87]
	ds_read_b128 v[144:147], v83 offset:10112
	s_waitcnt lgkmcnt(0)
	v_mfma_f32_16x16x32_bf16 v[178:181], v[144:147], v[4:7], v[102:105]
	v_mfma_f32_16x16x32_bf16 v[102:105], v[144:147], v[20:23], v[84:87]
	s_nop 1
	v_max_f32_e32 v83, v150, v151
	s_nop 0
	v_max_f32_e32 v84, v152, v153
	v_max_f32_e32 v85, v160, v161
	v_max3_f32 v85, v158, v159, v85
	v_max3_f32 v83, v83, v84, v85
	v_max_f32_e32 v84, v168, v169
	v_max_f32_e32 v86, v180, v180
	v_max_f32_e32 v85, v86, v181
	v_max3_f32 v84, v166, v167, v84
	v_max3_f32 v85, v178, v179, v85
	v_max3_f32 v83, v83, v84, v85
	s_waitcnt lgkmcnt(0)
	v_mov_b32_e32 v84, v83
	s_nop 1
	v_permlane16_swap_b32_e32 v83, v84
	v_max_f32_e32 v83, v83, v84
	v_mov_b32_e32 v84, v83
	s_nop 1
	v_permlane32_swap_b32_e32 v83, v84
	v_max3_f32 v176, v82, v83, v84
	v_sub_f32_e32 v82, v82, v176
	v_exp_f32_e32 v146, v82
	v_sub_f32_e32 v82, v150, v176
	v_exp_f32_e32 v142, v82
	v_sub_f32_e32 v82, v151, v176
	v_exp_f32_e32 v144, v82
	v_sub_f32_e32 v82, v152, v176
	v_exp_f32_e32 v150, v82
	v_sub_f32_e32 v82, v153, v176
	v_exp_f32_e32 v152, v82
	v_sub_f32_e32 v82, v158, v176
	v_exp_f32_e32 v156, v82
	v_sub_f32_e32 v82, v159, v176
	v_exp_f32_e32 v158, v82
	v_sub_f32_e32 v82, v160, v176
	v_exp_f32_e32 v160, v82
	v_sub_f32_e32 v82, v161, v176
	v_exp_f32_e32 v162, v82
	v_sub_f32_e32 v82, v166, v176
	v_exp_f32_e32 v164, v82
	v_sub_f32_e32 v82, v167, v176
	v_exp_f32_e32 v166, v82
	v_sub_f32_e32 v82, v168, v176
	v_exp_f32_e32 v168, v82
	v_sub_f32_e32 v82, v169, v176
	v_exp_f32_e32 v170, v82
	v_sub_f32_e32 v82, v178, v176
	v_exp_f32_e32 v172, v82
	v_sub_f32_e32 v82, v179, v176
	v_exp_f32_e32 v174, v82
	v_sub_f32_e32 v82, v180, v176
	v_exp_f32_e32 v178, v82
	v_sub_f32_e32 v82, v181, v176
	v_exp_f32_e32 v180, v82
	v_mul_f32_e32 v84, v68, v146
	v_mul_f32_e32 v85, v69, v146
	v_mul_f32_e32 v82, v66, v146
	v_mul_f32_e32 v83, v67, v146
	v_mul_f32_e32 v88, v72, v146
	v_mul_f32_e32 v89, v73, v146
	v_mul_f32_e32 v86, v70, v146
	v_mul_f32_e32 v87, v71, v146
	v_mul_f32_e32 v76, v76, v146
	v_mul_f32_e32 v77, v77, v146
	v_mul_f32_e32 v74, v74, v146
	v_mul_f32_e32 v75, v75, v146
	v_mul_f32_e32 v68, v80, v146
	v_mul_f32_e32 v69, v81, v146
	v_mul_f32_e32 v66, v78, v146
	v_mul_f32_e32 v67, v79, v146
	v_max_f32_e32 v145, v90, v91
	v_max_f32_e32 v147, v92, v93
	v_max_f32_e32 v151, v96, v97
	v_max3_f32 v151, v94, v95, v151
	v_max3_f32 v145, v145, v147, v151
	v_max_f32_e32 v147, v100, v101
	v_max_f32_e32 v151, v104, v105
	v_max3_f32 v147, v98, v99, v147
	v_max3_f32 v151, v102, v103, v151
	v_max3_f32 v145, v145, v147, v151
	v_cvt_pk_bf16_f32 v70, v142, v144
	v_cvt_pk_bf16_f32 v71, v150, v152
	v_cvt_pk_bf16_f32 v72, v156, v158
	v_cvt_pk_bf16_f32 v73, v160, v162
	s_waitcnt lgkmcnt(0)
	v_mov_b32_e32 v147, v145
	s_nop 1
	v_permlane16_swap_b32_e32 v145, v147
	v_max_f32_e32 v145, v145, v147
	v_mov_b32_e32 v147, v145
	s_nop 1
	v_permlane32_swap_b32_e32 v145, v147
	v_max3_f32 v177, v143, v145, v147
	v_sub_f32_e32 v143, v143, v177
	v_sub_f32_e32 v90, v90, v177
	v_exp_f32_e32 v147, v143
	v_exp_f32_e32 v143, v90
	v_sub_f32_e32 v90, v91, v177
	v_exp_f32_e32 v145, v90
	v_sub_f32_e32 v90, v92, v177
	v_exp_f32_e32 v151, v90
	v_sub_f32_e32 v90, v93, v177
	v_exp_f32_e32 v153, v90
	v_sub_f32_e32 v90, v94, v177
	v_exp_f32_e32 v157, v90
	v_sub_f32_e32 v90, v95, v177
	v_exp_f32_e32 v159, v90
	v_add_f32_e32 v90, 0, v142
	v_add_f32_e32 v91, 0, v143
	v_sub_f32_e32 v92, v96, v177
	v_add_f32_e32 v90, v144, v90
	v_add_f32_e32 v91, v145, v91
	v_exp_f32_e32 v161, v92
	v_add_f32_e32 v90, v150, v90
	v_add_f32_e32 v91, v151, v91
	v_sub_f32_e32 v92, v97, v177
	v_add_f32_e32 v90, v152, v90
	v_add_f32_e32 v91, v153, v91
	v_exp_f32_e32 v163, v92
	v_sub_f32_e32 v92, v98, v177
	v_add_f32_e32 v90, v156, v90
	v_add_f32_e32 v91, v157, v91
	v_exp_f32_e32 v165, v92
	v_sub_f32_e32 v92, v99, v177
	v_add_f32_e32 v90, v158, v90
	v_add_f32_e32 v91, v159, v91
	v_exp_f32_e32 v167, v92
	v_sub_f32_e32 v92, v100, v177
	v_exp_f32_e32 v169, v92
	v_sub_f32_e32 v92, v101, v177
	v_add_f32_e32 v90, v160, v90
	v_add_f32_e32 v91, v161, v91
	v_exp_f32_e32 v171, v92
	v_sub_f32_e32 v92, v102, v177
	v_add_f32_e32 v90, v162, v90
	v_add_f32_e32 v91, v163, v91
	v_exp_f32_e32 v173, v92
	v_sub_f32_e32 v92, v103, v177
	v_add_f32_e32 v90, v164, v90
	v_add_f32_e32 v91, v165, v91
	v_exp_f32_e32 v175, v92
	v_sub_f32_e32 v92, v104, v177
	v_add_f32_e32 v90, v166, v90
	v_add_f32_e32 v91, v167, v91
	v_exp_f32_e32 v179, v92
	v_sub_f32_e32 v92, v105, v177
	v_add_f32_e32 v90, v168, v90
	v_add_f32_e32 v91, v169, v91
	v_exp_f32_e32 v181, v92
	v_add_f32_e32 v90, v170, v90
	v_add_f32_e32 v91, v171, v91
	v_mov_b32_e32 v98, v147
	v_add_f32_e32 v90, v172, v90
	v_add_f32_e32 v91, v173, v91
	v_add3_u32 v142, s18, v127, v189
	ds_read_b64_tr_b16 v[216:217], v142 offset:13384
	ds_read_b64_tr_b16 v[218:219], v142 offset:15944
	ds_read_b64_tr_b16 v[212:213], v142 offset:13376
	ds_read_b64_tr_b16 v[214:215], v142 offset:15936
	v_add_f32_e32 v90, v174, v90
	v_add_f32_e32 v91, v175, v91
	v_mul_f32_e32 v92, v52, v98
	v_mul_f32_e32 v93, v53, v98
	v_add_f32_e32 v90, v178, v90
	v_add_f32_e32 v91, v179, v91
	v_mul_f32_e32 v96, v56, v98
	v_mul_f32_e32 v97, v57, v98
	v_add_f32_e32 v90, v180, v90
	v_add_f32_e32 v91, v181, v91
	v_mul_f32_e32 v94, v54, v98
	v_mul_f32_e32 v95, v55, v98
	v_pk_fma_f32 v[140:141], v[140:141], v[146:147], v[90:91]
	v_mul_f32_e32 v90, v50, v98
	v_mul_f32_e32 v91, v51, v98
	v_mul_f32_e32 v60, v60, v98
	v_mul_f32_e32 v61, v61, v98
	v_mul_f32_e32 v58, v58, v98
	v_mul_f32_e32 v59, v59, v98
	v_mul_f32_e32 v52, v64, v98
	v_mul_f32_e32 v53, v65, v98
	v_mul_f32_e32 v50, v62, v98
	v_mul_f32_e32 v51, v63, v98
	ds_read_b64_tr_b16 v[100:101], v142 offset:15872
	ds_read_b64_tr_b16 v[98:99], v142 offset:13312
	ds_read_b64_tr_b16 v[102:103], v142 offset:13320
	v_cvt_pk_bf16_f32 v54, v143, v145
	v_cvt_pk_bf16_f32 v55, v151, v153
	v_cvt_pk_bf16_f32 v56, v157, v159
	v_cvt_pk_bf16_f32 v57, v161, v163
	s_waitcnt lgkmcnt(1)
	v_mfma_f32_16x16x32_bf16 v[82:85], v[98:101], v[70:73], v[82:85]
	ds_read_b64_tr_b16 v[104:105], v142 offset:15880
	v_cvt_pk_bf16_f32 v78, v164, v166
	v_cvt_pk_bf16_f32 v79, v168, v170
	v_mfma_f32_16x16x32_bf16 v[90:93], v[98:101], v[54:57], v[90:93]
	v_cvt_pk_bf16_f32 v80, v172, v174
	v_cvt_pk_bf16_f32 v81, v178, v180
	s_waitcnt lgkmcnt(0)
	v_mfma_f32_16x16x32_bf16 v[74:77], v[212:215], v[70:73], v[74:77]
	v_cvt_pk_bf16_f32 v62, v165, v167
	v_cvt_pk_bf16_f32 v63, v169, v171
	v_cvt_pk_bf16_f32 v64, v173, v175
	v_mfma_f32_16x16x32_bf16 v[58:61], v[212:215], v[54:57], v[58:61]
	ds_read_b64_tr_b16 v[212:213], v142 offset:18432
	ds_read_b64_tr_b16 v[214:215], v142 offset:20992
	v_cvt_pk_bf16_f32 v65, v179, v181
	v_mov_b32_e32 v143, v177
	v_mfma_f32_16x16x32_bf16 v[86:89], v[102:105], v[70:73], v[86:89]
	ds_read_b64_tr_b16 v[220:221], v142 offset:18496
	ds_read_b64_tr_b16 v[222:223], v142 offset:21056
	v_mfma_f32_16x16x32_bf16 v[94:97], v[102:105], v[54:57], v[94:97]
	s_waitcnt lgkmcnt(0)
	v_mfma_f32_16x16x32_bf16 v[102:105], v[216:219], v[70:73], v[66:69]
	v_mfma_f32_16x16x32_bf16 v[98:101], v[216:219], v[54:57], v[50:53]
	s_nop 2
	ds_read_b64_tr_b16 v[54:55], v142 offset:18440
	ds_read_b64_tr_b16 v[56:57], v142 offset:21000
	s_waitcnt lgkmcnt(2)
	v_mfma_f32_16x16x32_bf16 v[66:69], v[212:215], v[78:81], v[82:85]
	s_nop 2
	s_waitcnt lgkmcnt(0)
	v_mfma_f32_16x16x32_bf16 v[74:77], v[220:223], v[78:81], v[74:77]
	v_mfma_f32_16x16x32_bf16 v[58:61], v[220:223], v[62:65], v[58:61]
	ds_read_b64_tr_b16 v[82:83], v142 offset:18504
	ds_read_b64_tr_b16 v[84:85], v142 offset:21064
	v_mfma_f32_16x16x32_bf16 v[50:53], v[212:215], v[62:65], v[90:93]
	v_mfma_f32_16x16x32_bf16 v[70:73], v[54:57], v[78:81], v[86:89]
	v_mfma_f32_16x16x32_bf16 v[54:57], v[54:57], v[62:65], v[94:97]
	s_waitcnt lgkmcnt(0)
	v_mfma_f32_16x16x32_bf16 v[78:81], v[82:85], v[78:81], v[102:105]
	v_mfma_f32_16x16x32_bf16 v[62:65], v[82:85], v[62:65], v[98:101]
	v_mov_b32_e32 v82, v176
	s_add_i32 s6, s46, -2
	s_cmp_ge_i32 s6, s52
	s_cbranch_scc1 .LBB0_1064
.LBB0_1078:
	s_and_b32 s6, s6, 3
	s_mulk_i32 s6, 0x5c00
	s_add_i32 s18, s6, 0
	v_add3_u32 v83, s18, v186, v188
	ds_read_b128 v[212:215], v83 offset:128
	ds_read_b128 v[84:87], v83
	ds_read_b128 v[92:95], v83 offset:64
	v_add3_u32 v127, s18, v127, v189
	s_waitcnt lgkmcnt(1)
	v_mfma_f32_16x16x32_bf16 v[88:91], v[84:87], v[8:11], 0
	ds_read_b128 v[98:101], v83 offset:3392
	ds_read_b128 v[102:105], v83 offset:6720
	ds_read_b128 v[144:147], v83 offset:10048
	v_mfma_f32_16x16x32_bf16 v[84:87], v[84:87], v[12:15], 0
	ds_read_b128 v[216:219], v83 offset:3328
	s_waitcnt lgkmcnt(3)
	v_mfma_f32_16x16x32_bf16 v[88:91], v[92:95], v[0:3], v[88:91]
	v_mfma_f32_16x16x32_bf16 v[84:87], v[92:95], v[16:19], v[84:87]
	s_waitcnt lgkmcnt(0)
	v_mfma_f32_16x16x32_bf16 v[150:153], v[212:215], v[4:7], v[88:91]
	v_mfma_f32_16x16x32_bf16 v[90:93], v[212:215], v[20:23], v[84:87]
	ds_read_b128 v[212:215], v83 offset:3456
	s_nop 3
	s_waitcnt lgkmcnt(0)
	v_mfma_f32_16x16x32_bf16 v[94:97], v[216:219], v[8:11], 0
	v_mfma_f32_16x16x32_bf16 v[84:87], v[216:219], v[12:15], 0
	ds_read_b128 v[216:219], v83 offset:6656
	v_mfma_f32_16x16x32_bf16 v[94:97], v[98:101], v[0:3], v[94:97]
	v_mfma_f32_16x16x32_bf16 v[84:87], v[98:101], v[16:19], v[84:87]
	s_waitcnt lgkmcnt(0)
	v_mfma_f32_16x16x32_bf16 v[158:161], v[212:215], v[4:7], v[94:97]
	v_mfma_f32_16x16x32_bf16 v[94:97], v[212:215], v[20:23], v[84:87]
	ds_read_b128 v[212:215], v83 offset:6784
	s_nop 3
	s_waitcnt lgkmcnt(0)
	v_mfma_f32_16x16x32_bf16 v[98:101], v[216:219], v[8:11], 0
	v_mfma_f32_16x16x32_bf16 v[84:87], v[216:219], v[12:15], 0
	ds_read_b128 v[216:219], v83 offset:9984
	v_mfma_f32_16x16x32_bf16 v[98:101], v[102:105], v[0:3], v[98:101]
	v_mfma_f32_16x16x32_bf16 v[84:87], v[102:105], v[16:19], v[84:87]
	s_waitcnt lgkmcnt(0)
	v_mfma_f32_16x16x32_bf16 v[166:169], v[212:215], v[4:7], v[98:101]
	v_mfma_f32_16x16x32_bf16 v[98:101], v[212:215], v[20:23], v[84:87]
	s_nop 3
	s_waitcnt lgkmcnt(0)
	v_mfma_f32_16x16x32_bf16 v[102:105], v[216:219], v[8:11], 0
	v_mfma_f32_16x16x32_bf16 v[84:87], v[216:219], v[12:15], 0
	v_mfma_f32_16x16x32_bf16 v[102:105], v[144:147], v[0:3], v[102:105]
	v_mfma_f32_16x16x32_bf16 v[84:87], v[144:147], v[16:19], v[84:87]
	ds_read_b64_tr_b16 v[212:213], v127 offset:13376
	ds_read_b64_tr_b16 v[214:215], v127 offset:15936
	ds_read_b128 v[144:147], v83 offset:10112
	s_waitcnt lgkmcnt(0)
	v_mfma_f32_16x16x32_bf16 v[176:179], v[144:147], v[4:7], v[102:105]
	v_mfma_f32_16x16x32_bf16 v[102:105], v[144:147], v[20:23], v[84:87]
	ds_read_b64_tr_b16 v[216:217], v127 offset:13384
	ds_read_b64_tr_b16 v[218:219], v127 offset:15944
	s_nop 1
	v_max_f32_e32 v83, v150, v151
	v_max_f32_e32 v84, v152, v153
	v_max_f32_e32 v85, v160, v161
	v_max3_f32 v85, v158, v159, v85
	v_max3_f32 v83, v83, v84, v85
	v_max_f32_e32 v84, v168, v169
	v_max_f32_e32 v86, v178, v178
	v_max_f32_e32 v85, v86, v179
	v_max3_f32 v84, v166, v167, v84
	v_max3_f32 v85, v176, v177, v85
	v_max3_f32 v83, v83, v84, v85
	s_waitcnt lgkmcnt(0)
	v_mov_b32_e32 v84, v83
	s_nop 1
	v_permlane16_swap_b32_e32 v83, v84
	v_max_f32_e32 v83, v83, v84
	v_mov_b32_e32 v84, v83
	s_nop 1
	v_permlane32_swap_b32_e32 v83, v84
	v_max3_f32 v174, v82, v83, v84
	v_sub_f32_e32 v82, v82, v174
	v_exp_f32_e32 v146, v82
	v_sub_f32_e32 v82, v150, v174
	v_exp_f32_e32 v142, v82
	v_sub_f32_e32 v82, v151, v174
	v_exp_f32_e32 v144, v82
	v_sub_f32_e32 v82, v152, v174
	v_exp_f32_e32 v150, v82
	v_sub_f32_e32 v82, v153, v174
	v_exp_f32_e32 v152, v82
	v_sub_f32_e32 v82, v158, v174
	v_exp_f32_e32 v156, v82
	v_sub_f32_e32 v82, v159, v174
	v_exp_f32_e32 v158, v82
	v_sub_f32_e32 v82, v160, v174
	v_exp_f32_e32 v160, v82
	v_sub_f32_e32 v82, v161, v174
	v_exp_f32_e32 v162, v82
	v_sub_f32_e32 v82, v166, v174
	v_exp_f32_e32 v164, v82
	v_sub_f32_e32 v82, v167, v174
	v_exp_f32_e32 v166, v82
	v_sub_f32_e32 v82, v168, v174
	v_exp_f32_e32 v168, v82
	v_sub_f32_e32 v82, v169, v174
	v_exp_f32_e32 v170, v82
	v_sub_f32_e32 v82, v176, v174
	v_exp_f32_e32 v172, v82
	v_sub_f32_e32 v82, v177, v174
	v_exp_f32_e32 v176, v82
	v_sub_f32_e32 v82, v178, v174
	v_exp_f32_e32 v178, v82
	v_sub_f32_e32 v82, v179, v174
	v_exp_f32_e32 v180, v82
	v_mul_f32_e32 v84, v68, v146
	v_mul_f32_e32 v85, v69, v146
	v_mul_f32_e32 v82, v66, v146
	v_mul_f32_e32 v83, v67, v146
	v_mul_f32_e32 v88, v72, v146
	v_mul_f32_e32 v89, v73, v146
	v_mul_f32_e32 v86, v70, v146
	v_mul_f32_e32 v87, v71, v146
	v_mul_f32_e32 v76, v76, v146
	v_mul_f32_e32 v77, v77, v146
	v_mul_f32_e32 v74, v74, v146
	v_mul_f32_e32 v75, v75, v146
	v_mul_f32_e32 v68, v80, v146
	v_mul_f32_e32 v69, v81, v146
	v_mul_f32_e32 v66, v78, v146
	v_mul_f32_e32 v67, v79, v146
	v_max_f32_e32 v145, v90, v91
	v_max_f32_e32 v147, v92, v93
	v_max_f32_e32 v151, v96, v97
	v_max3_f32 v151, v94, v95, v151
	v_max3_f32 v145, v145, v147, v151
	v_max_f32_e32 v147, v100, v101
	v_max_f32_e32 v151, v104, v105
	v_max3_f32 v147, v98, v99, v147
	v_max3_f32 v151, v102, v103, v151
	v_max3_f32 v145, v145, v147, v151
	v_cvt_pk_bf16_f32 v70, v142, v144
	v_cvt_pk_bf16_f32 v71, v150, v152
	v_cvt_pk_bf16_f32 v72, v156, v158
	v_cvt_pk_bf16_f32 v73, v160, v162
	s_waitcnt lgkmcnt(0)
	v_mov_b32_e32 v147, v145
	s_nop 1
	v_permlane16_swap_b32_e32 v145, v147
	v_max_f32_e32 v145, v145, v147
	v_mov_b32_e32 v147, v145
	s_nop 1
	v_permlane32_swap_b32_e32 v145, v147
	v_max3_f32 v175, v143, v145, v147
	v_sub_f32_e32 v143, v143, v175
	v_sub_f32_e32 v90, v90, v175
	v_exp_f32_e32 v147, v143
	v_exp_f32_e32 v143, v90
	v_sub_f32_e32 v90, v91, v175
	v_exp_f32_e32 v145, v90
	v_sub_f32_e32 v90, v92, v175
	v_exp_f32_e32 v151, v90
	v_sub_f32_e32 v90, v93, v175
	v_exp_f32_e32 v153, v90
	v_sub_f32_e32 v90, v94, v175
	v_exp_f32_e32 v157, v90
	v_sub_f32_e32 v90, v95, v175
	v_exp_f32_e32 v159, v90
	v_add_f32_e32 v90, 0, v142
	v_add_f32_e32 v91, 0, v143
	v_sub_f32_e32 v92, v96, v175
	v_add_f32_e32 v90, v144, v90
	v_add_f32_e32 v91, v145, v91
	v_exp_f32_e32 v161, v92
	v_add_f32_e32 v90, v150, v90
	v_add_f32_e32 v91, v151, v91
	v_sub_f32_e32 v92, v97, v175
	v_add_f32_e32 v90, v152, v90
	v_add_f32_e32 v91, v153, v91
	v_exp_f32_e32 v163, v92
	v_sub_f32_e32 v92, v98, v175
	v_add_f32_e32 v90, v156, v90
	v_add_f32_e32 v91, v157, v91
	v_exp_f32_e32 v165, v92
	v_sub_f32_e32 v92, v99, v175
	v_add_f32_e32 v90, v158, v90
	v_add_f32_e32 v91, v159, v91
	v_exp_f32_e32 v167, v92
	v_sub_f32_e32 v92, v100, v175
	v_exp_f32_e32 v169, v92
	v_sub_f32_e32 v92, v101, v175
	v_add_f32_e32 v90, v160, v90
	v_add_f32_e32 v91, v161, v91
	v_exp_f32_e32 v171, v92
	v_sub_f32_e32 v92, v102, v175
	v_add_f32_e32 v90, v162, v90
	v_add_f32_e32 v91, v163, v91
	v_exp_f32_e32 v173, v92
	v_sub_f32_e32 v92, v103, v175
	v_add_f32_e32 v90, v164, v90
	v_add_f32_e32 v91, v165, v91
	v_exp_f32_e32 v177, v92
	v_sub_f32_e32 v92, v104, v175
	v_add_f32_e32 v90, v166, v90
	v_add_f32_e32 v91, v167, v91
	v_exp_f32_e32 v179, v92
	v_sub_f32_e32 v92, v105, v175
	v_add_f32_e32 v90, v168, v90
	v_add_f32_e32 v91, v169, v91
	v_exp_f32_e32 v181, v92
	v_add_f32_e32 v90, v170, v90
	v_add_f32_e32 v91, v171, v91
	v_mov_b32_e32 v98, v147
	v_add_f32_e32 v90, v172, v90
	v_add_f32_e32 v91, v173, v91
	v_mul_f32_e32 v92, v52, v98
	v_mul_f32_e32 v93, v53, v98
	v_add_f32_e32 v90, v176, v90
	v_add_f32_e32 v91, v177, v91
	v_mul_f32_e32 v96, v56, v98
	v_mul_f32_e32 v97, v57, v98
	v_add_f32_e32 v90, v178, v90
	v_add_f32_e32 v91, v179, v91
	v_mul_f32_e32 v94, v54, v98
	v_mul_f32_e32 v95, v55, v98
	v_add_f32_e32 v90, v180, v90
	v_add_f32_e32 v91, v181, v91
	v_mul_f32_e32 v60, v60, v98
	v_mul_f32_e32 v61, v61, v98
	v_pk_fma_f32 v[140:141], v[140:141], v[146:147], v[90:91]
	v_mul_f32_e32 v90, v50, v98
	v_mul_f32_e32 v91, v51, v98
	v_mul_f32_e32 v58, v58, v98
	v_mul_f32_e32 v59, v59, v98
	v_mul_f32_e32 v52, v64, v98
	v_mul_f32_e32 v53, v65, v98
	v_mul_f32_e32 v50, v62, v98
	v_mul_f32_e32 v51, v63, v98
	ds_read_b64_tr_b16 v[100:101], v127 offset:15872
	ds_read_b64_tr_b16 v[98:99], v127 offset:13312
	ds_read_b64_tr_b16 v[102:103], v127 offset:13320
	v_cvt_pk_bf16_f32 v54, v143, v145
	v_cvt_pk_bf16_f32 v55, v151, v153
	v_cvt_pk_bf16_f32 v56, v157, v159
	v_cvt_pk_bf16_f32 v57, v161, v163
	s_waitcnt lgkmcnt(1)
	v_mfma_f32_16x16x32_bf16 v[82:85], v[98:101], v[70:73], v[82:85]
	ds_read_b64_tr_b16 v[104:105], v127 offset:15880
	v_cvt_pk_bf16_f32 v78, v164, v166
	v_cvt_pk_bf16_f32 v79, v168, v170
	v_mfma_f32_16x16x32_bf16 v[90:93], v[98:101], v[54:57], v[90:93]
	v_cvt_pk_bf16_f32 v80, v172, v176
	v_cvt_pk_bf16_f32 v81, v178, v180
	s_waitcnt lgkmcnt(0)
	v_mfma_f32_16x16x32_bf16 v[74:77], v[212:215], v[70:73], v[74:77]
	v_cvt_pk_bf16_f32 v62, v165, v167
	v_cvt_pk_bf16_f32 v63, v169, v171
	v_cvt_pk_bf16_f32 v64, v173, v177
	v_mfma_f32_16x16x32_bf16 v[58:61], v[212:215], v[54:57], v[58:61]
	ds_read_b64_tr_b16 v[212:213], v127 offset:18432
	ds_read_b64_tr_b16 v[214:215], v127 offset:20992
	v_cvt_pk_bf16_f32 v65, v179, v181
	v_mov_b32_e32 v143, v175
	v_mfma_f32_16x16x32_bf16 v[86:89], v[102:105], v[70:73], v[86:89]
	ds_read_b64_tr_b16 v[220:221], v127 offset:18496
	ds_read_b64_tr_b16 v[222:223], v127 offset:21056
	v_mfma_f32_16x16x32_bf16 v[94:97], v[102:105], v[54:57], v[94:97]
	s_waitcnt lgkmcnt(0)
	v_mfma_f32_16x16x32_bf16 v[102:105], v[216:219], v[70:73], v[66:69]
	v_mfma_f32_16x16x32_bf16 v[98:101], v[216:219], v[54:57], v[50:53]
	s_nop 2
	ds_read_b64_tr_b16 v[54:55], v127 offset:18440
	ds_read_b64_tr_b16 v[56:57], v127 offset:21000
	s_waitcnt lgkmcnt(2)
	v_mfma_f32_16x16x32_bf16 v[66:69], v[212:215], v[78:81], v[82:85]
	s_nop 2
	s_waitcnt lgkmcnt(0)
	v_mfma_f32_16x16x32_bf16 v[74:77], v[220:223], v[78:81], v[74:77]
	v_mfma_f32_16x16x32_bf16 v[58:61], v[220:223], v[62:65], v[58:61]
	ds_read_b64_tr_b16 v[82:83], v127 offset:18504
	ds_read_b64_tr_b16 v[84:85], v127 offset:21064
	v_mfma_f32_16x16x32_bf16 v[50:53], v[212:215], v[62:65], v[90:93]
	v_mfma_f32_16x16x32_bf16 v[70:73], v[54:57], v[78:81], v[86:89]
	v_mfma_f32_16x16x32_bf16 v[54:57], v[54:57], v[62:65], v[94:97]
	s_waitcnt lgkmcnt(0)
	v_mfma_f32_16x16x32_bf16 v[78:81], v[82:85], v[78:81], v[102:105]
	v_mfma_f32_16x16x32_bf16 v[62:65], v[82:85], v[62:65], v[98:101]
	v_mov_b32_e32 v82, v174
	s_branch .LBB0_1064
